# FFN_UP epilogue: own copy of the next-tile rstd tail with counted vmcnt(8) so the 8 epilogue stores are not drained before the next K-loop
# baseline (speedup 1.0000x reference)
; DI u32x2 pk4(f32x4 v) { u32x2 r; r.x = cvt_pk(v[0], v[1]); r.y = cvt_pk(v[2], v[3]); return r; }
; DI float fexp2(float x) { return __builtin_amdgcn_exp2f(x); }
; DI float frcp(float x) { return __builtin_amdgcn_rcpf(x); }
; DI void gemm_phase(LAS unsigned char* lds, const GemmDesc& d, float* __restrict__ X) {
;     ...
;     if (EPI_ON(EPI_FFN_UP)) {
; #pragma unroll
;       for (int ai = 0; ai < 2; ++ai)
; #pragma unroll
;         for (int m = 0; m < 4; ++m) {
;           const int row = pm * 256 + 128 * ai + 16 * m + rb; const float rs = rsl[128 * ai + 16 * m + rb]; const float c1 = -rs * LOG2E, c2 = rs * rs;
;           u32x2 hp[2];
; #pragma unroll
;           for (int n = 0; n < 2; ++n) {
;             const f32x4 G = acc[ai][0][m][n], U = acc[ai][1][m][n]; const f32x4 tt = G * c1; f32x4 ee;
; #pragma unroll
;             for (int j = 0; j < 4; ++j) ee[j] = fexp2(tt[j]);
;             const f32x4 dn = ee + 1.f; f32x4 rr;
; #pragma unroll
;             for (int j = 0; j < 4; ++j) rr[j] = frcp(dn[j]);
;             hp[n] = pk4((G * U) * (rr * c2));
;           }
;           { const int hc = pn * 128 + cb;
;             u32x4 hw; hw.x = hp[0].x; hw.y = hp[0].y; hw.z = hp[1].x; hw.w = hp[1].y;
;             *(u32x4*)(d.O0 + (size_t)(row >> 8) * (256 * FF) + (size_t)(hc >> 6) * (256 * 64) + (row & 255) * 64 + (hc & 63)) = hw; }
.LBB0_519:
	s_andn2_b64 vcc, exec, s[44:45]
	s_cbranch_vccnz .LBB0_542
	s_cmp_lg_u32 s24, 1
	s_mov_b64 s[44:45], -1
	s_cbranch_scc0 .LBB0_522
	v_lshl_add_u32 v141, v163, 2, s38
	ds_read_b32 v132, v141
	ds_read_b32 v133, v141 offset:64
	ds_read_b32 v134, v141 offset:128
	ds_read_b32 v135, v141 offset:192
	ds_read_b32 v136, v141 offset:512
	ds_read_b32 v137, v141 offset:576
	ds_read_b32 v138, v141 offset:640
	ds_read_b32 v139, v141 offset:704
	s_lshl_b32 s6, s68, 7
	v_lshl_add_u32 v0, s97, 8, v163
	s_or_b32 s6, s21, s6
	v_lshrrev_b32_e32 v0, 8, v0
	s_ashr_i32 s14, s6, 6
	v_mul_hi_i32_i24_e32 v131, 0x160000, v0
	v_mul_i32_i24_e32 v130, 0x160000, v0
	s_ashr_i32 s15, s14, 31
	v_lshl_add_u64 v[130:131], s[28:29], 0, v[130:131]
	s_lshl_b64 s[44:45], s[14:15], 15
	v_lshlrev_b32_e32 v0, 7, v163
	v_and_b32_e32 v144, 56, v182
	v_lshl_add_u64 v[130:131], v[130:131], 0, s[44:45]
	v_and_b32_e32 v0, 0x6780, v0
	v_lshl_add_u64 v[130:131], v[130:131], 0, v[0:1]
	v_lshlrev_b32_e32 v0, 1, v144
	v_mov_b32_e32 v144, 1.0
	v_lshl_add_u64 v[130:131], v[130:131], 0, v[0:1]
	v_mov_b32_e32 v145, 1.0
	s_mov_b32 s15, 0
	s_waitcnt lgkmcnt(0)
	v_mul_f32_e32 v140, 0xbfb8aa3b, v132
	v_mul_f32_e32 v142, v132, v132
	v_pk_mul_f32 v[118:119], v[126:127], v[118:119]
	v_pk_mul_f32 v[120:121], v[128:129], v[120:121]
	v_pk_mul_f32 v[114:115], v[122:123], v[114:115]
	v_pk_mul_f32 v[116:117], v[124:125], v[116:117]
	v_pk_mul_f32 v[126:127], v[126:127], v[140:141] op_sel_hi:[1,0]
	v_pk_mul_f32 v[128:129], v[128:129], v[140:141] op_sel_hi:[1,0]
	v_pk_mul_f32 v[122:123], v[122:123], v[140:141] op_sel_hi:[1,0]
	v_pk_mul_f32 v[124:125], v[124:125], v[140:141] op_sel_hi:[1,0]
	v_exp_f32_e32 v126, v126
	v_exp_f32_e32 v127, v127
	v_exp_f32_e32 v128, v128
	v_exp_f32_e32 v129, v129
	v_exp_f32_e32 v122, v122
	v_exp_f32_e32 v123, v123
	v_exp_f32_e32 v124, v124
	v_exp_f32_e32 v125, v125
	v_pk_add_f32 v[126:127], v[126:127], v[144:145]
	v_pk_add_f32 v[128:129], v[128:129], v[144:145]
	v_pk_add_f32 v[122:123], v[122:123], v[144:145]
	v_pk_add_f32 v[124:125], v[124:125], v[144:145]
	v_rcp_f32_e32 v126, v126
	v_rcp_f32_e32 v127, v127
	v_rcp_f32_e32 v128, v128
	v_rcp_f32_e32 v129, v129
	v_rcp_f32_e32 v122, v122
	v_rcp_f32_e32 v123, v123
	v_rcp_f32_e32 v124, v124
	v_rcp_f32_e32 v125, v125
	v_pk_mul_f32 v[126:127], v[142:143], v[126:127] op_sel_hi:[0,1]
	v_pk_mul_f32 v[128:129], v[142:143], v[128:129] op_sel_hi:[0,1]
	v_pk_mul_f32 v[122:123], v[142:143], v[122:123] op_sel_hi:[0,1]
	v_pk_mul_f32 v[124:125], v[142:143], v[124:125] op_sel_hi:[0,1]
	v_pk_mul_f32 v[126:127], v[118:119], v[126:127]
	v_pk_mul_f32 v[128:129], v[120:121], v[128:129]
	v_pk_mul_f32 v[122:123], v[114:115], v[122:123]
	v_pk_mul_f32 v[124:125], v[116:117], v[124:125]
	v_cvt_pk_bf16_f32 v126, v126, v127
	v_cvt_pk_bf16_f32 v127, v128, v129
	v_cvt_pk_bf16_f32 v128, v122, v123
	v_cvt_pk_bf16_f32 v129, v124, v125
	global_store_dwordx4 v[130:131], v[126:129], off
	v_mul_f32_e32 v140, 0xbfb8aa3b, v133
	v_mul_f32_e32 v142, v133, v133
	v_pk_mul_f32 v[102:103], v[110:111], v[102:103]
	v_pk_mul_f32 v[104:105], v[112:113], v[104:105]
	v_pk_mul_f32 v[98:99], v[106:107], v[98:99]
	v_pk_mul_f32 v[100:101], v[108:109], v[100:101]
	v_pk_mul_f32 v[110:111], v[110:111], v[140:141] op_sel_hi:[1,0]
	v_pk_mul_f32 v[112:113], v[112:113], v[140:141] op_sel_hi:[1,0]
	v_pk_mul_f32 v[106:107], v[106:107], v[140:141] op_sel_hi:[1,0]
	v_pk_mul_f32 v[108:109], v[108:109], v[140:141] op_sel_hi:[1,0]
	v_exp_f32_e32 v110, v110
	v_exp_f32_e32 v111, v111
	v_exp_f32_e32 v112, v112
	v_exp_f32_e32 v113, v113
	v_exp_f32_e32 v106, v106
	v_exp_f32_e32 v107, v107
	v_exp_f32_e32 v108, v108
	v_exp_f32_e32 v109, v109
	v_pk_add_f32 v[110:111], v[110:111], v[144:145]
	v_pk_add_f32 v[112:113], v[112:113], v[144:145]
	v_pk_add_f32 v[106:107], v[106:107], v[144:145]
	v_pk_add_f32 v[108:109], v[108:109], v[144:145]
	v_rcp_f32_e32 v110, v110
	v_rcp_f32_e32 v111, v111
	v_rcp_f32_e32 v112, v112
	v_rcp_f32_e32 v113, v113
	v_rcp_f32_e32 v106, v106
	v_rcp_f32_e32 v107, v107
	v_rcp_f32_e32 v108, v108
	v_rcp_f32_e32 v109, v109
	v_pk_mul_f32 v[110:111], v[142:143], v[110:111] op_sel_hi:[0,1]
	v_pk_mul_f32 v[112:113], v[142:143], v[112:113] op_sel_hi:[0,1]
	v_pk_mul_f32 v[106:107], v[142:143], v[106:107] op_sel_hi:[0,1]
	v_pk_mul_f32 v[108:109], v[142:143], v[108:109] op_sel_hi:[0,1]
	v_pk_mul_f32 v[110:111], v[102:103], v[110:111]
	v_pk_mul_f32 v[112:113], v[104:105], v[112:113]
	v_pk_mul_f32 v[106:107], v[98:99], v[106:107]
	v_pk_mul_f32 v[108:109], v[100:101], v[108:109]
	v_cvt_pk_bf16_f32 v110, v110, v111
	v_cvt_pk_bf16_f32 v111, v112, v113
	v_cvt_pk_bf16_f32 v112, v106, v107
	v_cvt_pk_bf16_f32 v113, v108, v109
	global_store_dwordx4 v[130:131], v[110:113], off offset:2048
	s_movk_i32 s14, 0x1000
	v_lshl_add_u64 v[114:115], v[130:131], 0, s[14:15]
	v_mul_f32_e32 v140, 0xbfb8aa3b, v134
	v_mul_f32_e32 v142, v134, v134
	v_pk_mul_f32 v[86:87], v[94:95], v[86:87]
	v_pk_mul_f32 v[88:89], v[96:97], v[88:89]
	v_pk_mul_f32 v[82:83], v[90:91], v[82:83]
	v_pk_mul_f32 v[84:85], v[92:93], v[84:85]
	v_pk_mul_f32 v[94:95], v[94:95], v[140:141] op_sel_hi:[1,0]
	v_pk_mul_f32 v[96:97], v[96:97], v[140:141] op_sel_hi:[1,0]
	v_pk_mul_f32 v[90:91], v[90:91], v[140:141] op_sel_hi:[1,0]
	v_pk_mul_f32 v[92:93], v[92:93], v[140:141] op_sel_hi:[1,0]
	v_exp_f32_e32 v94, v94
	v_exp_f32_e32 v95, v95
	v_exp_f32_e32 v96, v96
	v_exp_f32_e32 v97, v97
	v_exp_f32_e32 v90, v90
	v_exp_f32_e32 v91, v91
	v_exp_f32_e32 v92, v92
	v_exp_f32_e32 v93, v93
	v_pk_add_f32 v[94:95], v[94:95], v[144:145]
	v_pk_add_f32 v[96:97], v[96:97], v[144:145]
	v_pk_add_f32 v[90:91], v[90:91], v[144:145]
	v_pk_add_f32 v[92:93], v[92:93], v[144:145]
; DI u32x2 pk4(f32x4 v) { u32x2 r; r.x = cvt_pk(v[0], v[1]); r.y = cvt_pk(v[2], v[3]); return r; }
; DI float fexp2(float x) { return __builtin_amdgcn_exp2f(x); }
; DI float frcp(float x) { return __builtin_amdgcn_rcpf(x); }
; DI void gemm_phase(LAS unsigned char* lds, const GemmDesc& d, float* __restrict__ X) {
;     ...
;           const int row = pm * 256 + 128 * ai + 16 * m + rb; const float rs = rsl[128 * ai + 16 * m + rb]; const float c1 = -rs * LOG2E, c2 = rs * rs;
;           u32x2 hp[2];
; #pragma unroll
;           for (int n = 0; n < 2; ++n) {
;             const f32x4 G = acc[ai][0][m][n], U = acc[ai][1][m][n]; const f32x4 tt = G * c1; f32x4 ee;
; #pragma unroll
;             for (int j = 0; j < 4; ++j) ee[j] = fexp2(tt[j]);
;             const f32x4 dn = ee + 1.f; f32x4 rr;
; #pragma unroll
;             for (int j = 0; j < 4; ++j) rr[j] = frcp(dn[j]);
;             hp[n] = pk4((G * U) * (rr * c2));
;           }
;           { const int hc = pn * 128 + cb;
;             u32x4 hw; hw.x = hp[0].x; hw.y = hp[0].y; hw.z = hp[1].x; hw.w = hp[1].y;
;             *(u32x4*)(d.O0 + (size_t)(row >> 8) * (256 * FF) + (size_t)(hc >> 6) * (256 * 64) + (row & 255) * 64 + (hc & 63)) = hw; }
	v_rcp_f32_e32 v94, v94
	v_rcp_f32_e32 v95, v95
	v_rcp_f32_e32 v96, v96
	v_rcp_f32_e32 v97, v97
	v_rcp_f32_e32 v90, v90
	v_rcp_f32_e32 v91, v91
	v_rcp_f32_e32 v92, v92
	v_rcp_f32_e32 v93, v93
	v_pk_mul_f32 v[94:95], v[142:143], v[94:95] op_sel_hi:[0,1]
	v_pk_mul_f32 v[96:97], v[142:143], v[96:97] op_sel_hi:[0,1]
	v_pk_mul_f32 v[90:91], v[142:143], v[90:91] op_sel_hi:[0,1]
	v_pk_mul_f32 v[92:93], v[142:143], v[92:93] op_sel_hi:[0,1]
	v_pk_mul_f32 v[94:95], v[86:87], v[94:95]
	v_pk_mul_f32 v[96:97], v[88:89], v[96:97]
	v_pk_mul_f32 v[90:91], v[82:83], v[90:91]
	v_pk_mul_f32 v[92:93], v[84:85], v[92:93]
	v_cvt_pk_bf16_f32 v94, v94, v95
	v_cvt_pk_bf16_f32 v95, v96, v97
	v_cvt_pk_bf16_f32 v96, v90, v91
	v_cvt_pk_bf16_f32 v97, v92, v93
	global_store_dwordx4 v[114:115], v[94:97], off
	v_mul_f32_e32 v140, 0xbfb8aa3b, v135
	v_mul_f32_e32 v142, v135, v135
	v_pk_mul_f32 v[70:71], v[78:79], v[70:71]
	v_pk_mul_f32 v[72:73], v[80:81], v[72:73]
	v_pk_mul_f32 v[66:67], v[74:75], v[66:67]
	v_pk_mul_f32 v[68:69], v[76:77], v[68:69]
	v_pk_mul_f32 v[78:79], v[78:79], v[140:141] op_sel_hi:[1,0]
	v_pk_mul_f32 v[80:81], v[80:81], v[140:141] op_sel_hi:[1,0]
	v_pk_mul_f32 v[74:75], v[74:75], v[140:141] op_sel_hi:[1,0]
	v_pk_mul_f32 v[76:77], v[76:77], v[140:141] op_sel_hi:[1,0]
	v_exp_f32_e32 v78, v78
	v_exp_f32_e32 v79, v79
	v_exp_f32_e32 v80, v80
	v_exp_f32_e32 v81, v81
	v_exp_f32_e32 v74, v74
	v_exp_f32_e32 v75, v75
	v_exp_f32_e32 v76, v76
	v_exp_f32_e32 v77, v77
	v_pk_add_f32 v[78:79], v[78:79], v[144:145]
	v_pk_add_f32 v[80:81], v[80:81], v[144:145]
	v_pk_add_f32 v[74:75], v[74:75], v[144:145]
	v_pk_add_f32 v[76:77], v[76:77], v[144:145]
	v_rcp_f32_e32 v78, v78
	v_rcp_f32_e32 v79, v79
	v_rcp_f32_e32 v80, v80
	v_rcp_f32_e32 v81, v81
	v_rcp_f32_e32 v74, v74
	v_rcp_f32_e32 v75, v75
	v_rcp_f32_e32 v76, v76
	v_rcp_f32_e32 v77, v77
	v_pk_mul_f32 v[78:79], v[142:143], v[78:79] op_sel_hi:[0,1]
	v_pk_mul_f32 v[80:81], v[142:143], v[80:81] op_sel_hi:[0,1]
	v_pk_mul_f32 v[74:75], v[142:143], v[74:75] op_sel_hi:[0,1]
	v_pk_mul_f32 v[76:77], v[142:143], v[76:77] op_sel_hi:[0,1]
	v_pk_mul_f32 v[78:79], v[70:71], v[78:79]
	v_pk_mul_f32 v[80:81], v[72:73], v[80:81]
	v_pk_mul_f32 v[74:75], v[66:67], v[74:75]
	v_pk_mul_f32 v[76:77], v[68:69], v[76:77]
	v_cvt_pk_bf16_f32 v78, v78, v79
	v_cvt_pk_bf16_f32 v79, v80, v81
	v_cvt_pk_bf16_f32 v80, v74, v75
	v_cvt_pk_bf16_f32 v81, v76, v77
	global_store_dwordx4 v[114:115], v[78:81], off offset:2048
	s_movk_i32 s14, 0x4000
	v_lshl_add_u64 v[116:117], v[130:131], 0, s[14:15]
	v_mul_f32_e32 v140, 0xbfb8aa3b, v136
	v_mul_f32_e32 v142, v136, v136
	v_pk_mul_f32 v[54:55], v[62:63], v[54:55]
	v_pk_mul_f32 v[56:57], v[64:65], v[56:57]
	v_pk_mul_f32 v[50:51], v[58:59], v[50:51]
	v_pk_mul_f32 v[52:53], v[60:61], v[52:53]
	v_pk_mul_f32 v[62:63], v[62:63], v[140:141] op_sel_hi:[1,0]
	v_pk_mul_f32 v[64:65], v[64:65], v[140:141] op_sel_hi:[1,0]
	v_pk_mul_f32 v[58:59], v[58:59], v[140:141] op_sel_hi:[1,0]
	v_pk_mul_f32 v[60:61], v[60:61], v[140:141] op_sel_hi:[1,0]
	v_exp_f32_e32 v62, v62
	v_exp_f32_e32 v63, v63
	v_exp_f32_e32 v64, v64
	v_exp_f32_e32 v65, v65
	v_exp_f32_e32 v58, v58
	v_exp_f32_e32 v59, v59
	v_exp_f32_e32 v60, v60
	v_exp_f32_e32 v61, v61
	v_pk_add_f32 v[62:63], v[62:63], v[144:145]
	v_pk_add_f32 v[64:65], v[64:65], v[144:145]
	v_pk_add_f32 v[58:59], v[58:59], v[144:145]
	v_pk_add_f32 v[60:61], v[60:61], v[144:145]
	v_rcp_f32_e32 v62, v62
	v_rcp_f32_e32 v63, v63
	v_rcp_f32_e32 v64, v64
	v_rcp_f32_e32 v65, v65
	v_rcp_f32_e32 v58, v58
	v_rcp_f32_e32 v59, v59
	v_rcp_f32_e32 v60, v60
	v_rcp_f32_e32 v61, v61
	v_pk_mul_f32 v[62:63], v[142:143], v[62:63] op_sel_hi:[0,1]
	v_pk_mul_f32 v[64:65], v[142:143], v[64:65] op_sel_hi:[0,1]
	v_pk_mul_f32 v[58:59], v[142:143], v[58:59] op_sel_hi:[0,1]
	v_pk_mul_f32 v[60:61], v[142:143], v[60:61] op_sel_hi:[0,1]
	v_pk_mul_f32 v[62:63], v[54:55], v[62:63]
	v_pk_mul_f32 v[64:65], v[56:57], v[64:65]
	v_pk_mul_f32 v[58:59], v[50:51], v[58:59]
	v_pk_mul_f32 v[60:61], v[52:53], v[60:61]
	v_cvt_pk_bf16_f32 v62, v62, v63
	v_cvt_pk_bf16_f32 v63, v64, v65
	v_cvt_pk_bf16_f32 v64, v58, v59
	v_cvt_pk_bf16_f32 v65, v60, v61
	global_store_dwordx4 v[116:117], v[62:65], off
	v_mul_f32_e32 v140, 0xbfb8aa3b, v137
	v_mul_f32_e32 v142, v137, v137
	v_pk_mul_f32 v[38:39], v[46:47], v[38:39]
	v_pk_mul_f32 v[40:41], v[48:49], v[40:41]
	v_pk_mul_f32 v[34:35], v[42:43], v[34:35]
	v_pk_mul_f32 v[36:37], v[44:45], v[36:37]
	v_pk_mul_f32 v[46:47], v[46:47], v[140:141] op_sel_hi:[1,0]
	v_pk_mul_f32 v[48:49], v[48:49], v[140:141] op_sel_hi:[1,0]
	v_pk_mul_f32 v[42:43], v[42:43], v[140:141] op_sel_hi:[1,0]
	v_pk_mul_f32 v[44:45], v[44:45], v[140:141] op_sel_hi:[1,0]
	v_exp_f32_e32 v46, v46
	v_exp_f32_e32 v47, v47
	v_exp_f32_e32 v48, v48
	v_exp_f32_e32 v49, v49
	v_exp_f32_e32 v42, v42
	v_exp_f32_e32 v43, v43
	v_exp_f32_e32 v44, v44
	v_exp_f32_e32 v45, v45
; #define LAS __attribute__((address_space(3)))
; DI u32x2 pk4(f32x4 v) { u32x2 r; r.x = cvt_pk(v[0], v[1]); r.y = cvt_pk(v[2], v[3]); return r; }
; DI float fexp2(float x) { return __builtin_amdgcn_exp2f(x); }
; DI float frcp(float x) { return __builtin_amdgcn_rcpf(x); }
; DI void gemm_phase(LAS unsigned char* lds, const GemmDesc& d, float* __restrict__ X) {
;     ...
;           const int row = pm * 256 + 128 * ai + 16 * m + rb; const float rs = rsl[128 * ai + 16 * m + rb]; const float c1 = -rs * LOG2E, c2 = rs * rs;
;           u32x2 hp[2];
; #pragma unroll
;           for (int n = 0; n < 2; ++n) {
;             const f32x4 G = acc[ai][0][m][n], U = acc[ai][1][m][n]; const f32x4 tt = G * c1; f32x4 ee;
; #pragma unroll
;             for (int j = 0; j < 4; ++j) ee[j] = fexp2(tt[j]);
;             const f32x4 dn = ee + 1.f; f32x4 rr;
; #pragma unroll
;             for (int j = 0; j < 4; ++j) rr[j] = frcp(dn[j]);
;             hp[n] = pk4((G * U) * (rr * c2));
;           }
;           { const int hc = pn * 128 + cb;
;             u32x4 hw; hw.x = hp[0].x; hw.y = hp[0].y; hw.z = hp[1].x; hw.w = hp[1].y;
;             *(u32x4*)(d.O0 + (size_t)(row >> 8) * (256 * FF) + (size_t)(hc >> 6) * (256 * 64) + (row & 255) * 64 + (hc & 63)) = hw; }
;     ...
;     if (nrs) ((LAS float*)(lds + 131072 + ((ui + 1) & 1) * 1024))[ktid] = rsqrtf(((q0 + q1) + (q2 + q3)) * d.inv_dim + EPS);
	v_pk_add_f32 v[46:47], v[46:47], v[144:145]
	v_pk_add_f32 v[48:49], v[48:49], v[144:145]
	v_pk_add_f32 v[42:43], v[42:43], v[144:145]
	v_pk_add_f32 v[44:45], v[44:45], v[144:145]
	v_rcp_f32_e32 v46, v46
	v_rcp_f32_e32 v47, v47
	v_rcp_f32_e32 v48, v48
	v_rcp_f32_e32 v49, v49
	v_rcp_f32_e32 v42, v42
	v_rcp_f32_e32 v43, v43
	v_rcp_f32_e32 v44, v44
	v_rcp_f32_e32 v45, v45
	v_pk_mul_f32 v[46:47], v[142:143], v[46:47] op_sel_hi:[0,1]
	v_pk_mul_f32 v[48:49], v[142:143], v[48:49] op_sel_hi:[0,1]
	v_pk_mul_f32 v[42:43], v[142:143], v[42:43] op_sel_hi:[0,1]
	v_pk_mul_f32 v[44:45], v[142:143], v[44:45] op_sel_hi:[0,1]
	v_pk_mul_f32 v[46:47], v[38:39], v[46:47]
	v_pk_mul_f32 v[48:49], v[40:41], v[48:49]
	v_pk_mul_f32 v[42:43], v[34:35], v[42:43]
	v_pk_mul_f32 v[44:45], v[36:37], v[44:45]
	v_cvt_pk_bf16_f32 v46, v46, v47
	v_cvt_pk_bf16_f32 v47, v48, v49
	v_cvt_pk_bf16_f32 v48, v42, v43
	v_cvt_pk_bf16_f32 v49, v44, v45
	global_store_dwordx4 v[116:117], v[46:49], off offset:2048
	s_movk_i32 s14, 0x5000
	v_lshl_add_u64 v[118:119], v[130:131], 0, s[14:15]
	v_mul_f32_e32 v140, 0xbfb8aa3b, v138
	v_mul_f32_e32 v142, v138, v138
	v_pk_mul_f32 v[22:23], v[30:31], v[22:23]
	v_pk_mul_f32 v[24:25], v[32:33], v[24:25]
	v_pk_mul_f32 v[18:19], v[26:27], v[18:19]
	v_pk_mul_f32 v[20:21], v[28:29], v[20:21]
	v_pk_mul_f32 v[30:31], v[30:31], v[140:141] op_sel_hi:[1,0]
	v_pk_mul_f32 v[32:33], v[32:33], v[140:141] op_sel_hi:[1,0]
	v_pk_mul_f32 v[26:27], v[26:27], v[140:141] op_sel_hi:[1,0]
	v_pk_mul_f32 v[28:29], v[28:29], v[140:141] op_sel_hi:[1,0]
	v_exp_f32_e32 v30, v30
	v_exp_f32_e32 v31, v31
	v_exp_f32_e32 v32, v32
	v_exp_f32_e32 v33, v33
	v_exp_f32_e32 v26, v26
	v_exp_f32_e32 v27, v27
	v_exp_f32_e32 v28, v28
	v_exp_f32_e32 v29, v29
	v_pk_add_f32 v[30:31], v[30:31], v[144:145]
	v_pk_add_f32 v[32:33], v[32:33], v[144:145]
	v_pk_add_f32 v[26:27], v[26:27], v[144:145]
	v_pk_add_f32 v[28:29], v[28:29], v[144:145]
	v_rcp_f32_e32 v30, v30
	v_rcp_f32_e32 v31, v31
	v_rcp_f32_e32 v32, v32
	v_rcp_f32_e32 v33, v33
	v_rcp_f32_e32 v26, v26
	v_rcp_f32_e32 v27, v27
	v_rcp_f32_e32 v28, v28
	v_rcp_f32_e32 v29, v29
	v_pk_mul_f32 v[30:31], v[142:143], v[30:31] op_sel_hi:[0,1]
	v_pk_mul_f32 v[32:33], v[142:143], v[32:33] op_sel_hi:[0,1]
	v_pk_mul_f32 v[26:27], v[142:143], v[26:27] op_sel_hi:[0,1]
	v_pk_mul_f32 v[28:29], v[142:143], v[28:29] op_sel_hi:[0,1]
	v_pk_mul_f32 v[30:31], v[22:23], v[30:31]
	v_pk_mul_f32 v[32:33], v[24:25], v[32:33]
	v_pk_mul_f32 v[26:27], v[18:19], v[26:27]
	v_pk_mul_f32 v[28:29], v[20:21], v[28:29]
	v_cvt_pk_bf16_f32 v30, v30, v31
	v_cvt_pk_bf16_f32 v31, v32, v33
	v_cvt_pk_bf16_f32 v32, v26, v27
	v_cvt_pk_bf16_f32 v33, v28, v29
	global_store_dwordx4 v[118:119], v[30:33], off
	v_mul_f32_e32 v140, 0xbfb8aa3b, v139
	v_mul_f32_e32 v142, v139, v139
	v_pk_mul_f32 v[6:7], v[14:15], v[6:7]
	v_pk_mul_f32 v[8:9], v[16:17], v[8:9]
	v_pk_mul_f32 v[2:3], v[10:11], v[2:3]
	v_pk_mul_f32 v[4:5], v[12:13], v[4:5]
	v_pk_mul_f32 v[14:15], v[14:15], v[140:141] op_sel_hi:[1,0]
	v_pk_mul_f32 v[16:17], v[16:17], v[140:141] op_sel_hi:[1,0]
	v_pk_mul_f32 v[10:11], v[10:11], v[140:141] op_sel_hi:[1,0]
	v_pk_mul_f32 v[12:13], v[12:13], v[140:141] op_sel_hi:[1,0]
	v_exp_f32_e32 v14, v14
	v_exp_f32_e32 v15, v15
	v_exp_f32_e32 v16, v16
	v_exp_f32_e32 v17, v17
	v_exp_f32_e32 v10, v10
	v_exp_f32_e32 v11, v11
	v_exp_f32_e32 v12, v12
	v_exp_f32_e32 v13, v13
	v_pk_add_f32 v[14:15], v[14:15], v[144:145]
	v_pk_add_f32 v[16:17], v[16:17], v[144:145]
	v_pk_add_f32 v[10:11], v[10:11], v[144:145]
	v_pk_add_f32 v[12:13], v[12:13], v[144:145]
	v_rcp_f32_e32 v14, v14
	v_rcp_f32_e32 v15, v15
	v_rcp_f32_e32 v16, v16
	v_rcp_f32_e32 v17, v17
	v_rcp_f32_e32 v10, v10
	v_rcp_f32_e32 v11, v11
	v_rcp_f32_e32 v12, v12
	v_rcp_f32_e32 v13, v13
	v_pk_mul_f32 v[14:15], v[142:143], v[14:15] op_sel_hi:[0,1]
	v_pk_mul_f32 v[16:17], v[142:143], v[16:17] op_sel_hi:[0,1]
	v_pk_mul_f32 v[10:11], v[142:143], v[10:11] op_sel_hi:[0,1]
	v_pk_mul_f32 v[12:13], v[142:143], v[12:13] op_sel_hi:[0,1]
	v_pk_mul_f32 v[14:15], v[6:7], v[14:15]
	v_pk_mul_f32 v[16:17], v[8:9], v[16:17]
	v_pk_mul_f32 v[10:11], v[2:3], v[10:11]
	v_pk_mul_f32 v[12:13], v[4:5], v[12:13]
	v_cvt_pk_bf16_f32 v14, v14, v15
	v_cvt_pk_bf16_f32 v15, v16, v17
	v_cvt_pk_bf16_f32 v16, v10, v11
	v_cvt_pk_bf16_f32 v17, v12, v13
	global_store_dwordx4 v[118:119], v[14:17], off offset:2048
	s_and_saveexec_b64 s[44:45], s[88:89]
	s_cbranch_execz .LBB0_544
	s_waitcnt vmcnt(8) lgkmcnt(0)
	v_pk_add_f32 v[2:3], v[160:161], v[158:159]
	s_lshl_b32 s6, s36, 10
	v_add_f32_e32 v0, v2, v3
	v_fma_f32 v0, s62, v0, v195
	v_cmp_gt_f32_e32 vcc, s57, v0
	v_mul_f32_e32 v2, 0x4b800000, v0
	s_and_b32 s6, s6, 0x400
	v_cndmask_b32_e32 v0, v0, v2, vcc
	v_rsq_f32_e32 v0, v0
	s_nop 0
	v_mul_f32_e32 v2, 0x45800000, v0
	v_cndmask_b32_e32 v0, v0, v2, vcc
	v_add_u32_e32 v2, s6, v176
	ds_write_b32 v2, v0
	s_branch .LBB0_544
